# forget-logit tile (4 real columns of 256) runs a K-loop copy that issues only the MFMAs and fragment reads feeding the stored accumulators, on top of v24
# baseline (speedup 1.0000x reference)
.LBB0_175:
	s_ashr_i32 s67, s66, 31
	s_lshl_b64 s[34:35], s[66:67], 19
	s_add_u32 s70, s53, s34
	s_addc_u32 s71, s68, s35
	s_ashr_i32 s57, s56, 31
	s_lshl_b64 s[34:35], s[56:57], 19
	s_add_u32 s72, s3, s34
	s_addc_u32 s73, s45, s35
	s_andn2_b64 vcc, exec, s[40:41]
	s_cbranch_vccnz .LBB0_197
	s_and_b64 s[34:35], s[4:5], exec
	s_cselect_b32 s34, s71, s7
	s_cselect_b32 s35, s70, s6
	s_cselect_b32 s47, s73, s65
	s_cselect_b32 s55, s72, s64
	s_add_u32 s6, s6, 0x40080
	s_addc_u32 s7, s7, 0
	s_add_u32 s57, s64, 0x100
	v_mov_b32_e32 v2, 0
	s_addc_u32 s59, s65, 0
	s_mov_b32 s64, 0
	v_mov_b32_e32 v3, v2
	v_mov_b32_e32 v4, v2
	v_mov_b32_e32 v5, v2
	v_mov_b32_e32 v6, v2
	v_mov_b32_e32 v7, v2
	v_mov_b32_e32 v8, v2
	v_mov_b32_e32 v9, v2
	v_mov_b32_e32 v18, v2
	v_mov_b32_e32 v19, v2
	v_mov_b32_e32 v20, v2
	v_mov_b32_e32 v21, v2
	v_mov_b32_e32 v22, v2
	v_mov_b32_e32 v23, v2
	v_mov_b32_e32 v24, v2
	v_mov_b32_e32 v25, v2
	v_mov_b32_e32 v34, v2
	v_mov_b32_e32 v35, v2
	v_mov_b32_e32 v36, v2
	v_mov_b32_e32 v37, v2
	v_mov_b32_e32 v38, v2
	v_mov_b32_e32 v39, v2
	v_mov_b32_e32 v40, v2
	v_mov_b32_e32 v41, v2
	v_mov_b32_e32 v50, v2
	v_mov_b32_e32 v51, v2
	v_mov_b32_e32 v52, v2
	v_mov_b32_e32 v53, v2
	v_mov_b32_e32 v54, v2
	v_mov_b32_e32 v55, v2
	v_mov_b32_e32 v56, v2
	v_mov_b32_e32 v57, v2
	v_mov_b32_e32 v10, v2
	v_mov_b32_e32 v11, v2
	v_mov_b32_e32 v12, v2
	v_mov_b32_e32 v13, v2
	v_mov_b32_e32 v14, v2
	v_mov_b32_e32 v15, v2
	v_mov_b32_e32 v16, v2
	v_mov_b32_e32 v17, v2
	v_mov_b32_e32 v26, v2
	v_mov_b32_e32 v27, v2
	v_mov_b32_e32 v28, v2
	v_mov_b32_e32 v29, v2
	v_mov_b32_e32 v30, v2
	v_mov_b32_e32 v31, v2
	v_mov_b32_e32 v32, v2
	v_mov_b32_e32 v33, v2
	v_mov_b32_e32 v42, v2
	v_mov_b32_e32 v43, v2
	v_mov_b32_e32 v44, v2
	v_mov_b32_e32 v45, v2
	v_mov_b32_e32 v46, v2
	v_mov_b32_e32 v47, v2
	v_mov_b32_e32 v48, v2
	v_mov_b32_e32 v49, v2
	v_mov_b32_e32 v58, v2
	v_mov_b32_e32 v59, v2
	v_mov_b32_e32 v60, v2
	v_mov_b32_e32 v61, v2
	v_mov_b32_e32 v62, v2
	v_mov_b32_e32 v63, v2
	v_mov_b32_e32 v64, v2
	v_mov_b32_e32 v65, v2
	v_mov_b32_e32 v66, v2
	v_mov_b32_e32 v67, v2
	v_mov_b32_e32 v68, v2
	v_mov_b32_e32 v69, v2
	v_mov_b32_e32 v70, v2
	v_mov_b32_e32 v71, v2
	v_mov_b32_e32 v72, v2
	v_mov_b32_e32 v73, v2
	v_mov_b32_e32 v82, v2
	v_mov_b32_e32 v83, v2
	v_mov_b32_e32 v84, v2
	v_mov_b32_e32 v85, v2
	v_mov_b32_e32 v86, v2
	v_mov_b32_e32 v87, v2
	v_mov_b32_e32 v88, v2
	v_mov_b32_e32 v89, v2
	v_mov_b32_e32 v98, v2
	v_mov_b32_e32 v99, v2
	v_mov_b32_e32 v100, v2
	v_mov_b32_e32 v101, v2
	v_mov_b32_e32 v102, v2
	v_mov_b32_e32 v103, v2
	v_mov_b32_e32 v104, v2
	v_mov_b32_e32 v105, v2
	v_mov_b32_e32 v114, v2
	v_mov_b32_e32 v115, v2
	v_mov_b32_e32 v116, v2
	v_mov_b32_e32 v117, v2
	v_mov_b32_e32 v118, v2
	v_mov_b32_e32 v119, v2
	v_mov_b32_e32 v120, v2
	v_mov_b32_e32 v121, v2
	v_mov_b32_e32 v74, v2
	v_mov_b32_e32 v75, v2
	v_mov_b32_e32 v76, v2
	v_mov_b32_e32 v77, v2
	v_mov_b32_e32 v78, v2
	v_mov_b32_e32 v79, v2
	v_mov_b32_e32 v80, v2
	v_mov_b32_e32 v81, v2
	v_mov_b32_e32 v90, v2
	v_mov_b32_e32 v91, v2
	v_mov_b32_e32 v92, v2
	v_mov_b32_e32 v93, v2
	v_mov_b32_e32 v94, v2
	v_mov_b32_e32 v95, v2
	v_mov_b32_e32 v96, v2
	v_mov_b32_e32 v97, v2
	v_mov_b32_e32 v106, v2
	v_mov_b32_e32 v107, v2
	v_mov_b32_e32 v108, v2
	v_mov_b32_e32 v109, v2
	v_mov_b32_e32 v110, v2
	v_mov_b32_e32 v111, v2
	v_mov_b32_e32 v112, v2
	v_mov_b32_e32 v113, v2
	v_mov_b32_e32 v122, v2
	v_mov_b32_e32 v123, v2
	v_mov_b32_e32 v124, v2
	v_mov_b32_e32 v125, v2
	v_mov_b32_e32 v126, v2
	v_mov_b32_e32 v127, v2
	v_mov_b32_e32 v128, v2
	v_mov_b32_e32 v129, v2
	s_cmp_eq_u32 s25, 18
	s_cbranch_scc1 .Lfl_entry

.Lfl_kexit:
	s_and_b64 vcc, exec, s[50:51]
	s_cbranch_vccz .LBB0_180

.Lfl_entry:
	v_readfirstlane_b32 s99, v236
	s_bfe_u32 s99, s99, 0x20006
.Lfl_kloop:
	s_add_i32 s67, s64, 2
	s_add_u32 s65, s6, 0xfffc0080
	s_addc_u32 s80, s7, -1
	s_add_i32 s81, 0, 0x10000
	s_cmp_eq_u32 s49, s64
	s_cselect_b32 s93, s34, s80
	s_cselect_b32 s92, s35, s65
	v_add_u32_e32 v0, s81, v145
	s_cselect_b32 s65, s47, s59
	s_cselect_b32 s64, s55, s57
	s_add_i32 s94, 0, 0x14000
	s_cmp_lg_u32 s99, 0
	s_cbranch_scc1 .Lfl_1
	ds_read_b128 v[130:133], v0
	ds_read_b128 v[156:159], v0 offset:1024
	ds_read_b128 v[160:163], v0 offset:2048
	ds_read_b128 v[164:167], v0 offset:3072
.Lfl_1:
	v_add_u32_e32 v0, s94, v145
	s_cmp_lg_u32 s99, 0
	s_cbranch_scc1 .Lfl_2
	ds_read_b128 v[168:171], v0
	ds_read_b128 v[172:175], v0 offset:1024
	ds_read_b128 v[176:179], v0 offset:2048
	ds_read_b128 v[180:183], v0 offset:3072
.Lfl_2:
	v_lshl_add_u64 v[208:209], s[6:7], 0, v[148:149]
	s_add_i32 m0, s28, 0xc000
	s_cmp_lg_u32 s99, 0
	s_cbranch_scc1 .Lfl_3
	ds_read_b128 v[188:191], v186
	ds_read_b128 v[192:195], v186 offset:1024
	ds_read_b128 v[196:199], v186 offset:2048
	ds_read_b128 v[200:203], v186 offset:3072
	ds_read_b128 v[204:207], v186 offset:4096
	ds_read_b128 v[214:217], v186 offset:5120
	ds_read_b128 v[218:221], v186 offset:6144
	ds_read_b128 v[222:225], v186 offset:7168
.Lfl_3:
	global_load_lds_dwordx4 v[208:209], off
	v_lshl_add_u64 v[208:209], s[6:7], 0, v[150:151]
	s_add_i32 m0, s28, 0xe000
	s_nop 0
	global_load_lds_dwordx4 v[208:209], off
	s_waitcnt vmcnt(8)
	s_waitcnt lgkmcnt(0)
	s_barrier
	s_cmp_lg_u32 s99, 0
	s_cbranch_scc1 .Lfl_4
	s_setprio 1
	s_waitcnt lgkmcnt(0)
	v_mfma_f32_16x16x32_bf16 v[126:129], v[130:133], v[188:191], v[126:129]
	v_mfma_f32_16x16x32_bf16 v[110:113], v[130:133], v[196:199], v[110:113]
	v_mfma_f32_16x16x32_bf16 v[94:97], v[130:133], v[204:207], v[94:97]
	v_mfma_f32_16x16x32_bf16 v[78:81], v[130:133], v[218:221], v[78:81]
	v_mfma_f32_16x16x32_bf16 v[126:129], v[156:159], v[192:195], v[126:129]
	v_mfma_f32_16x16x32_bf16 v[110:113], v[156:159], v[200:203], v[110:113]
	v_mfma_f32_16x16x32_bf16 v[94:97], v[156:159], v[214:217], v[94:97]
	v_mfma_f32_16x16x32_bf16 v[78:81], v[156:159], v[222:225], v[78:81]
	s_setprio 0
.Lfl_4:
	s_barrier
	s_add_i32 s80, s81, s97
	v_lshl_add_u64 v[208:209], s[64:65], 0, v[138:139]
	s_mov_b32 m0, s80
	s_cmp_lg_u32 s99, 0
	s_cbranch_scc1 .Lfl_5
	ds_read_b128 v[188:191], v186 offset:16384
	ds_read_b128 v[192:195], v186 offset:17408
	ds_read_b128 v[196:199], v186 offset:18432
	ds_read_b128 v[200:203], v186 offset:19456
	ds_read_b128 v[204:207], v186 offset:20480
	ds_read_b128 v[214:217], v186 offset:21504
	ds_read_b128 v[218:221], v186 offset:22528
	ds_read_b128 v[222:225], v186 offset:23552
.Lfl_5:
	global_load_lds_dwordx4 v[208:209], off
	s_add_i32 m0, s80, 0x2000
	s_add_u32 s80, s64, 0x40000
	v_lshl_add_u64 v[226:227], s[64:65], 0, v[134:135]
	s_addc_u32 s81, s65, 0
	s_add_i32 s94, s94, s97
	global_load_lds_dwordx4 v[226:227], off
	v_lshl_add_u64 v[228:229], s[80:81], 0, v[138:139]
	s_mov_b32 m0, s94
	v_lshl_add_u64 v[230:231], s[92:93], 0, v[136:137]
	global_load_lds_dwordx4 v[228:229], off
	v_lshl_add_u64 v[228:229], s[80:81], 0, v[134:135]
	s_add_i32 m0, s94, 0x2000
	s_nop 0
	global_load_lds_dwordx4 v[228:229], off
	v_lshl_add_u64 v[228:229], s[92:93], 0, v[140:141]
	s_mov_b32 m0, s28
	s_nop 0
	global_load_lds_dwordx4 v[228:229], off
	s_mov_b32 m0, s29
	s_nop 0
	global_load_lds_dwordx4 v[230:231], off
	s_waitcnt vmcnt(8)
	s_waitcnt lgkmcnt(0)
	s_barrier
	s_cmp_lg_u32 s99, 0
	s_cbranch_scc1 .Lfl_6
	s_setprio 1
	s_waitcnt lgkmcnt(0)
	v_mfma_f32_16x16x32_bf16 v[62:65], v[130:133], v[188:191], v[62:65]
	v_mfma_f32_16x16x32_bf16 v[46:49], v[130:133], v[196:199], v[46:49]
	v_mfma_f32_16x16x32_bf16 v[30:33], v[130:133], v[204:207], v[30:33]
	v_mfma_f32_16x16x32_bf16 v[14:17], v[130:133], v[218:221], v[14:17]
	v_mfma_f32_16x16x32_bf16 v[62:65], v[156:159], v[192:195], v[62:65]
	v_mfma_f32_16x16x32_bf16 v[46:49], v[156:159], v[200:203], v[46:49]
	v_mfma_f32_16x16x32_bf16 v[30:33], v[156:159], v[214:217], v[30:33]
	v_mfma_f32_16x16x32_bf16 v[14:17], v[156:159], v[222:225], v[14:17]
	s_setprio 0
.Lfl_6:
	s_barrier
	s_add_i32 s94, 0, 0x18000
	v_add_u32_e32 v0, s94, v145
	s_add_i32 s95, 0, 0x1c000
	s_cmp_lg_u32 s99, 0
	s_cbranch_scc1 .Lfl_7
	ds_read_b128 v[130:133], v0
	ds_read_b128 v[156:159], v0 offset:1024
	ds_read_b128 v[160:163], v0 offset:2048
	ds_read_b128 v[164:167], v0 offset:3072
.Lfl_7:
	v_add_u32_e32 v0, s95, v145
	s_cmp_lg_u32 s99, 0
	s_cbranch_scc1 .Lfl_8
	ds_read_b128 v[168:171], v0
	ds_read_b128 v[172:175], v0 offset:1024
	ds_read_b128 v[176:179], v0 offset:2048
	ds_read_b128 v[180:183], v0 offset:3072
.Lfl_8:
	s_add_u32 s80, s92, 0x40000
	s_addc_u32 s81, s93, 0
	s_mov_b32 m0, s31
	v_lshl_add_u64 v[232:233], s[80:81], 0, v[140:141]
	s_cmp_lg_u32 s99, 0
	s_cbranch_scc1 .Lfl_9
	ds_read_b128 v[188:191], v186 offset:32768
	ds_read_b128 v[192:195], v186 offset:33792
	ds_read_b128 v[196:199], v186 offset:34816
	ds_read_b128 v[200:203], v186 offset:35840
	ds_read_b128 v[204:207], v186 offset:36864
	ds_read_b128 v[214:217], v186 offset:37888
	ds_read_b128 v[218:221], v186 offset:38912
	ds_read_b128 v[222:225], v186 offset:39936
.Lfl_9:
	global_load_lds_dwordx4 v[232:233], off
	v_lshl_add_u64 v[232:233], s[80:81], 0, v[136:137]
	s_mov_b32 m0, s26
	s_nop 0
	global_load_lds_dwordx4 v[232:233], off
	s_waitcnt vmcnt(8)
	s_waitcnt lgkmcnt(0)
	s_barrier
	s_cmp_lg_u32 s99, 0
	s_cbranch_scc1 .Lfl_10
	s_setprio 1
	s_waitcnt lgkmcnt(0)
	v_mfma_f32_16x16x32_bf16 v[126:129], v[130:133], v[188:191], v[126:129]
	v_mfma_f32_16x16x32_bf16 v[110:113], v[130:133], v[196:199], v[110:113]
	v_mfma_f32_16x16x32_bf16 v[94:97], v[130:133], v[204:207], v[94:97]
	v_mfma_f32_16x16x32_bf16 v[78:81], v[130:133], v[218:221], v[78:81]
	v_mfma_f32_16x16x32_bf16 v[126:129], v[156:159], v[192:195], v[126:129]
	v_mfma_f32_16x16x32_bf16 v[110:113], v[156:159], v[200:203], v[110:113]
	v_mfma_f32_16x16x32_bf16 v[94:97], v[156:159], v[214:217], v[94:97]
	v_mfma_f32_16x16x32_bf16 v[78:81], v[156:159], v[222:225], v[78:81]
	s_setprio 0
.Lfl_10:
	s_barrier
	s_add_i32 s80, s94, s97
	v_lshl_add_u64 v[208:209], v[208:209], 0, s[78:79]
	s_mov_b32 m0, s80
	s_cmp_lg_u32 s99, 0
	s_cbranch_scc1 .Lfl_11
	ds_read_b128 v[188:191], v186 offset:49152
	ds_read_b128 v[192:195], v186 offset:50176
	ds_read_b128 v[196:199], v186 offset:51200
	ds_read_b128 v[200:203], v186 offset:52224
	ds_read_b128 v[204:207], v186 offset:53248
	ds_read_b128 v[214:217], v186 offset:54272
	ds_read_b128 v[218:221], v186 offset:55296
	ds_read_b128 v[222:225], v186 offset:56320
.Lfl_11:
	global_load_lds_dwordx4 v[208:209], off
	s_add_i32 m0, s80, 0x2000
	s_add_u32 s64, s64, 0x40080
	v_lshl_add_u64 v[208:209], v[226:227], 0, s[78:79]
	s_addc_u32 s65, s65, 0
	s_add_i32 s80, s95, s97
	global_load_lds_dwordx4 v[208:209], off
	v_lshl_add_u64 v[208:209], s[64:65], 0, v[138:139]
	s_mov_b32 m0, s80
	s_nop 0
	global_load_lds_dwordx4 v[208:209], off
	v_lshl_add_u64 v[208:209], s[64:65], 0, v[134:135]
	s_add_i32 m0, s80, 0x2000
	s_nop 0
	global_load_lds_dwordx4 v[208:209], off
	v_lshl_add_u64 v[208:209], v[228:229], 0, s[78:79]
	s_mov_b32 m0, s89
	s_nop 0
	global_load_lds_dwordx4 v[208:209], off
	v_lshl_add_u64 v[208:209], v[230:231], 0, s[78:79]
	s_mov_b32 m0, s8
	s_nop 0
	global_load_lds_dwordx4 v[208:209], off
	s_waitcnt vmcnt(8)
	s_waitcnt lgkmcnt(0)
	s_barrier
	s_cmp_lg_u32 s99, 0
	s_cbranch_scc1 .Lfl_12
	s_setprio 1
	s_waitcnt lgkmcnt(0)
	v_mfma_f32_16x16x32_bf16 v[62:65], v[130:133], v[188:191], v[62:65]
	v_mfma_f32_16x16x32_bf16 v[46:49], v[130:133], v[196:199], v[46:49]
	v_mfma_f32_16x16x32_bf16 v[30:33], v[130:133], v[204:207], v[30:33]
	v_mfma_f32_16x16x32_bf16 v[14:17], v[130:133], v[218:221], v[14:17]
	v_mfma_f32_16x16x32_bf16 v[62:65], v[156:159], v[192:195], v[62:65]
	v_mfma_f32_16x16x32_bf16 v[46:49], v[156:159], v[200:203], v[46:49]
	v_mfma_f32_16x16x32_bf16 v[30:33], v[156:159], v[214:217], v[30:33]
	v_mfma_f32_16x16x32_bf16 v[14:17], v[156:159], v[222:225], v[14:17]
	s_setprio 0
.Lfl_12:
	s_barrier
	s_add_u32 s6, s6, 0x100
	s_addc_u32 s7, s7, 0
	s_add_u32 s57, s57, 0x100
	s_addc_u32 s59, s59, 0
	s_cmp_ge_i32 s67, s44
	s_mov_b32 s64, s67
	s_cbranch_scc0 .Lfl_kloop
	s_branch .Lfl_kexit
